# lever 1: QKV L0 prologue compiler vmcnt(0) after the 8-piece LDS-DMA burst -> vmcnt(8) (WAW guard only); the hand-written vmcnt(2) that follows is unchanged
# speedup vs baseline: 1.0025x; 1.0025x over previous
; #define PG8_STAGE(bufoff, gbase, voff) do { _Pragma("unroll") for (int _i = 0; _i < 2; ++_i) \
;         __builtin_amdgcn_global_load_lds((const unsigned*)((const char*)(gbase) + (voff)[_i]), (PG8_LAS unsigned*)(lds + (bufoff) + ldsw + _i * 8192), 16, 0, 0); } while (0)
; #define PG8_WAIT_V(n) asm volatile("s_waitcnt vmcnt(" #n ")" ::: "memory")
; #define PG8_BAR __builtin_amdgcn_s_barrier()
; template <class Epi, class Sched, bool ALIGN_EPI = false, bool SP2 = false>
; __device__ __forceinline__ void gemm_phase(PG8_LAS unsigned char* lds, const Gemm g, const Sched& S, const Epi& E) {
;     ...
;     const unsigned ldsw = (unsigned)wid * 1024u;
;     const int aoff = lds_byte(wr * 64 + fr, fq * 8), boff = lds_byte(wc * 32 + fr, fq * 8);
;     ...
;         PG8_STAGE(PG8_SB(0, 0), cB, voffB); PG8_STAGE(PG8_SB(0, 1), cB + hstep, voffB); PG8_STAGE(PG8_SA(0, 0), cA, voffA); PG8_STAGE(PG8_SA(0, 1), cA + hstep, voffA);
;         if (wr == 1) PG8_BAR;
;         PG8_WAIT_V(2); PG8_BAR;
;         PG8_STAGE(PG8_SB(1, 0), cB + kstep, voffB); PG8_STAGE(PG8_SA(1, 0), cA + kstep, voffA); PG8_STAGE(PG8_SB(1, 1), cB + hstep + kstep, voffB);
;         PG8_WAIT_V(6); PG8_BAR;
.LBB0_263:
	v_mov_b32_e32 v137, v0
	v_lshl_add_u64 v[10:11], s[22:23], 0, v[136:137]
	s_waitcnt vmcnt(8)
	v_mov_b32_e32 v15, v0
	v_readlane_b32 s24, v254, 49
	s_lshl_b32 s14, s14, 5
	v_lshl_add_u64 v[12:13], s[22:23], 0, v[14:15]
	v_mov_b32_e32 v139, v0
	v_readlane_b32 s25, v254, 50
	s_and_b32 s28, s14, 0x60
	s_add_i32 m0, s10, 0x18000
	v_lshl_add_u64 v[10:11], v[10:11], 0, s[34:35]
	v_lshl_add_u64 v[18:19], s[24:25], 0, v[138:139]
	v_mov_b32_e32 v135, v0
	s_lshl_b32 s27, s15, 6
	s_lshl_b32 s13, s15, 13
	s_lshl_b32 s16, s28, 7
	s_waitcnt vmcnt(2)
	s_barrier
	global_load_lds_dwordx4 v[10:11], off
	v_lshl_add_u64 v[10:11], v[12:13], 0, s[34:35]
	s_add_i32 m0, s10, 0x1a000
	s_add_i32 s29, s10, 0x8000
	s_add_i32 s33, s10, 0xa000
	v_lshl_add_u64 v[20:21], s[24:25], 0, v[134:135]
	global_load_lds_dwordx4 v[10:11], off
	v_lshl_add_u64 v[10:11], v[18:19], 0, s[34:35]
	s_mov_b32 m0, s29
	s_add_u32 s14, s22, 0x40080
	global_load_lds_dwordx4 v[10:11], off
	v_lshl_add_u64 v[10:11], v[20:21], 0, s[34:35]
	s_mov_b32 m0, s33
	s_addc_u32 s15, s23, 0
	global_load_lds_dwordx4 v[10:11], off
	s_add_i32 m0, s10, 0x1c000
	v_lshl_add_u64 v[10:11], s[14:15], 0, v[136:137]
	global_load_lds_dwordx4 v[10:11], off
	v_lshl_add_u64 v[10:11], s[14:15], 0, v[14:15]
	s_add_i32 m0, s10, 0x1e000
	v_lshrrev_b32_e32 v9, 1, v2
	global_load_lds_dwordx4 v[10:11], off
	v_and_b32_e32 v17, 24, v9
	v_and_b32_e32 v1, 15, v2
	v_lshlrev_b32_e32 v9, 1, v17
	v_lshlrev_b32_e32 v2, 2, v2
	v_lshl_or_b32 v9, v1, 6, v9
	v_and_b32_e32 v2, 32, v2
	v_bitop3_b32 v10, v9, s13, v2 bitop3:0xde
	v_bitop3_b32 v154, v9, s16, v2 bitop3:0xde
	v_lshlrev_b32_e32 v2, 14, v7
	v_and_b32_e32 v2, 0xffff8000, v2
	v_lshl_add_u32 v2, v6, 11, v2
	v_and_b32_e32 v6, 1, v7
	v_lshl_or_b32 v2, v6, 6, v2
	v_lshl_add_u32 v140, v8, 1, v2
	v_lshlrev_b32_e32 v2, 14, v3
	v_and_b32_e32 v2, 0xffff8000, v2
	s_waitcnt vmcnt(6)
	v_lshl_add_u32 v2, v4, 11, v2
	v_and_b32_e32 v3, 1, v3
	s_cmpk_lt_u32 s12, 0x100
	v_lshl_or_b32 v2, v3, 6, v2
	v_readlane_b32 s12, v254, 39
	s_cselect_b64 s[14:15], -1, 0
	v_mov_b32_e32 v141, v0
	v_lshl_add_u32 v142, v5, 1, v2
	v_mov_b32_e32 v143, v0
	s_mov_b32 s49, 0
	v_add_u32_e32 v155, 0, v10
	v_readlane_b32 s58, v254, 29
	s_mov_b32 s71, s12
	s_barrier
	v_readlane_b32 s13, v254, 40
	s_branch .LBB0_266
